# w9: dead WINROWS stores removed; NSA prompt tiles: K/V LDS reads hoisted (hazard pad kept) and score copies removed via register-swapped non-cut path; peeled first K-iteration on all GEMM sites
# baseline (speedup 1.0000x reference)
; DI float fexp2(float x) { return __builtin_amdgcn_exp2f(x); }
; DI float xhalf_max(float v) { return fmaxf(v, __shfl_xor(v, 32)); }
; DI float xhalf_sum(float v) { return v + __shfl_xor(v, 32); }
; DI void tile_online(AState& st, const LAS bf16* Kt, int KP, const LAS bf16* Vt, int VP, const bf16x8 (&qf)[4], int kbase, int lo, int hi, bool flag, int r, int h) {
;     ...
;         for (int reg = 0; reg < 16; ++reg) mx = fmaxf(mx, s[reg]);
;     }
;     mx = any ? mx : -__builtin_inff();
;     mx = xhalf_max(mx);
;     if (__ballot(mx > st.m + 5.5f) != 0ull) {
;         const float mn2 = fmaxf(st.m, mx), alpha = fexp2((st.m - mn2) * LOG2E);
;         st.l = st.l * alpha; st.o0 = st.o0 * alpha; st.o1 = st.o1 * alpha; st.m = mn2;
;     }
;     const float mn = st.m;
;     const float bias = any ? -mn * LOG2E : -__builtin_inff();
;     f32x2 sum2 = {0.f, 0.f}; const f32x2 b2 = {bias, bias}, l2 = {LOG2E, LOG2E};
; #pragma unroll
;     for (int reg = 0; reg < 16; reg += 2) { f32x2 t = {s[reg], s[reg + 1]}; t = __builtin_elementwise_fma(t, l2, b2);
;         t[0] = fexp2(t[0]); t[1] = fexp2(t[1]); s[reg] = t[0]; s[reg + 1] = t[1]; sum2 = sum2 + t; }
;     st.l += xhalf_sum(sum2[0] + sum2[1]);
;     pv_tile32(st.o0, st.o1, Vt, VP, s, r + 32 * h);
.LBB0_1648:
	s_nop 7
	v_max3_f32 v36, v52, s40, v53
	v_max3_f32 v36, v36, v54, v55
	v_max3_f32 v36, v36, v56, v57
	v_max3_f32 v36, v36, v58, v59
	v_max3_f32 v36, v36, v60, v61
	v_max3_f32 v36, v36, v62, v63
	v_max3_f32 v36, v36, v64, v65
	v_max3_f32 v116, v36, v66, v67
	v_cndmask_b32_e64 v36, v231, v116, s[2:3]
	ds_bpermute_b32 v37, v110, v36
	v_max_f32_e32 v36, v36, v36
	s_waitcnt lgkmcnt(0)
	v_max_f32_e32 v37, v37, v37
	v_max_f32_e32 v36, v36, v37
	v_add_f32_e32 v37, 0x40b00000, v115
	v_cmp_gt_f32_e32 vcc, v36, v37
	s_cbranch_vccz .Lnc_exp_0
	v_max_f32_e32 v36, v36, v36
	v_max_f32_e32 v37, v115, v115
	v_max_f32_e32 v37, v37, v36
	v_sub_f32_e32 v36, v115, v37
	v_mul_f32_e32 v36, 0x3fb8aa3b, v36
	v_exp_f32_e32 v36, v36
	v_mov_b32_e32 v115, v37
	v_mul_f32_e32 v113, v113, v36
	v_pk_mul_f32 v[34:35], v[34:35], v[36:37] op_sel_hi:[1,0]
	v_pk_mul_f32 v[32:33], v[32:33], v[36:37] op_sel_hi:[1,0]
	v_pk_mul_f32 v[30:31], v[30:31], v[36:37] op_sel_hi:[1,0]
	v_pk_mul_f32 v[28:29], v[28:29], v[36:37] op_sel_hi:[1,0]
	v_pk_mul_f32 v[26:27], v[26:27], v[36:37] op_sel_hi:[1,0]
	v_pk_mul_f32 v[24:25], v[24:25], v[36:37] op_sel_hi:[1,0]
	v_pk_mul_f32 v[22:23], v[22:23], v[36:37] op_sel_hi:[1,0]
	v_pk_mul_f32 v[20:21], v[20:21], v[36:37] op_sel_hi:[1,0]
	v_pk_mul_f32 v[18:19], v[18:19], v[36:37] op_sel_hi:[1,0]
	v_pk_mul_f32 v[16:17], v[16:17], v[36:37] op_sel_hi:[1,0]
	v_pk_mul_f32 v[14:15], v[14:15], v[36:37] op_sel_hi:[1,0]
	v_pk_mul_f32 v[12:13], v[12:13], v[36:37] op_sel_hi:[1,0]
	v_pk_mul_f32 v[10:11], v[10:11], v[36:37] op_sel_hi:[1,0]
	v_pk_mul_f32 v[8:9], v[8:9], v[36:37] op_sel_hi:[1,0]
	v_pk_mul_f32 v[6:7], v[6:7], v[36:37] op_sel_hi:[1,0]
	v_pk_mul_f32 v[4:5], v[4:5], v[36:37] op_sel_hi:[1,0]
.Lnc_exp_0:
	v_mul_f32_e32 v36, 0xbfb8aa3b, v115
	v_cndmask_b32_e64 v36, v231, v36, s[2:3]
	v_pk_fma_f32 v[52:53], v[52:53], s[38:39], v[36:37] op_sel_hi:[1,0,0]
	v_pk_fma_f32 v[54:55], v[54:55], s[38:39], v[36:37] op_sel_hi:[1,0,0]
	v_exp_f32_e32 v52, v52
	v_exp_f32_e32 v53, v53
	v_exp_f32_e32 v54, v54
	v_exp_f32_e32 v55, v55
	v_pk_fma_f32 v[56:57], v[56:57], s[38:39], v[36:37] op_sel_hi:[1,0,0]
	v_pk_fma_f32 v[58:59], v[58:59], s[38:39], v[36:37] op_sel_hi:[1,0,0]
	v_exp_f32_e32 v56, v56
	v_exp_f32_e32 v57, v57
	v_exp_f32_e32 v58, v58
	v_exp_f32_e32 v59, v59
	v_pk_add_f32 v[38:39], v[52:53], 0 op_sel_hi:[1,0]
	v_cvt_pk_bf16_f32 v52, v52, v53
	v_pk_add_f32 v[38:39], v[54:55], v[38:39]
	v_cvt_pk_bf16_f32 v53, v54, v55
	v_pk_add_f32 v[38:39], v[56:57], v[38:39]
	v_cvt_pk_bf16_f32 v54, v56, v57
	v_pk_add_f32 v[38:39], v[58:59], v[38:39]
	v_cvt_pk_bf16_f32 v55, v58, v59
	s_nop 1
	s_waitcnt lgkmcnt(0)
	v_mfma_f32_32x32x16_bf16 v[20:35], v[126:129], v[52:55], v[20:35]
	v_fma_f32 v60, v60, s38, v36
	v_fma_f32 v61, v61, s38, v36
	v_fma_f32 v62, v62, s38, v36
	v_fma_f32 v63, v63, s38, v36
	v_pk_fma_f32 v[64:65], v[64:65], s[38:39], v[36:37] op_sel_hi:[1,0,0]
	v_pk_fma_f32 v[66:67], v[66:67], s[38:39], v[36:37] op_sel_hi:[1,0,0]
	v_exp_f32_e32 v60, v60
	v_exp_f32_e32 v61, v61
	v_exp_f32_e32 v62, v62
	v_exp_f32_e32 v63, v63
	v_exp_f32_e32 v64, v64
	v_exp_f32_e32 v65, v65
	v_exp_f32_e32 v66, v66
	v_exp_f32_e32 v67, v67
	s_waitcnt lgkmcnt(0)
	v_mfma_f32_32x32x16_bf16 v[4:19], v[130:133], v[52:55], v[4:19]
	v_cvt_pk_bf16_f32 v52, v60, v61
	v_cvt_pk_bf16_f32 v53, v62, v63
	v_cvt_pk_bf16_f32 v54, v64, v65
	v_cvt_pk_bf16_f32 v55, v66, v67
	v_pk_add_f32 v[38:39], v[60:61], v[38:39]
	s_waitcnt lgkmcnt(0)
	v_mfma_f32_32x32x16_bf16 v[20:35], v[134:137], v[52:55], v[20:35]
	v_add_f32_e64 v38, v62, v38
	v_add_f32_e64 v39, v63, v39
	v_add_f32_e64 v38, v64, v38
	v_add_f32_e64 v39, v65, v39
	v_pk_add_f32 v[36:37], v[66:67], v[38:39]
	s_nop 0
	v_add_f32_e32 v36, v36, v37
	s_waitcnt lgkmcnt(0)
	v_mfma_f32_32x32x16_bf16 v[4:19], v[138:141], v[52:55], v[4:19]
	ds_bpermute_b32 v37, v110, v36
	s_waitcnt lgkmcnt(0)
	v_add_f32_e32 v36, v36, v37
	v_add_f32_e32 v113, v113, v36
	s_branch .LBB0_1652

; DI float fexp2(float x) { return __builtin_amdgcn_exp2f(x); }
; DI float xhalf_sum(float v) { return v + __shfl_xor(v, 32); }
; DI void tile_online(AState& st, const LAS bf16* Kt, int KP, const LAS bf16* Vt, int VP, const bf16x8 (&qf)[4], int kbase, int lo, int hi, bool flag, int r, int h) {
;     ...
;     const float mn = st.m;
;     const float bias = any ? -mn * LOG2E : -__builtin_inff();
;     f32x2 sum2 = {0.f, 0.f}; const f32x2 b2 = {bias, bias}, l2 = {LOG2E, LOG2E};
; #pragma unroll
;     for (int reg = 0; reg < 16; reg += 2) { f32x2 t = {s[reg], s[reg + 1]}; t = __builtin_elementwise_fma(t, l2, b2);
;         t[0] = fexp2(t[0]); t[1] = fexp2(t[1]); s[reg] = t[0]; s[reg + 1] = t[1]; sum2 = sum2 + t; }
;     st.l += xhalf_sum(sum2[0] + sum2[1]);
;     pv_tile32(st.o0, st.o1, Vt, VP, s, r + 32 * h);
.LBB0_1651:
	v_mul_f32_e32 v52, 0xbfb8aa3b, v115
	v_cndmask_b32_e64 v52, v231, v52, s[2:3]
	v_pk_fma_f32 v[36:37], v[36:37], s[38:39], v[52:53] op_sel_hi:[1,0,0]
	v_pk_fma_f32 v[38:39], v[38:39], s[38:39], v[52:53] op_sel_hi:[1,0,0]
	v_exp_f32_e32 v36, v36
	v_exp_f32_e32 v37, v37
	v_exp_f32_e32 v38, v38
	v_exp_f32_e32 v39, v39
	v_pk_fma_f32 v[40:41], v[40:41], s[38:39], v[52:53] op_sel_hi:[1,0,0]
	v_pk_fma_f32 v[42:43], v[42:43], s[38:39], v[52:53] op_sel_hi:[1,0,0]
	v_exp_f32_e32 v40, v40
	v_exp_f32_e32 v41, v41
	v_exp_f32_e32 v42, v42
	v_exp_f32_e32 v43, v43
	v_pk_add_f32 v[54:55], v[36:37], 0 op_sel_hi:[1,0]
	v_cvt_pk_bf16_f32 v36, v36, v37
	v_pk_add_f32 v[54:55], v[38:39], v[54:55]
	v_cvt_pk_bf16_f32 v37, v38, v39
	v_pk_add_f32 v[54:55], v[40:41], v[54:55]
	v_cvt_pk_bf16_f32 v38, v40, v41
	v_pk_add_f32 v[54:55], v[42:43], v[54:55]
	v_cvt_pk_bf16_f32 v39, v42, v43
	s_nop 1
	s_waitcnt lgkmcnt(0)
	v_mfma_f32_32x32x16_bf16 v[20:35], v[126:129], v[36:39], v[20:35]
	v_fma_f32 v44, v44, s38, v52
	v_fma_f32 v45, v45, s38, v52
	v_fma_f32 v46, v46, s38, v52
	v_fma_f32 v47, v47, s38, v52
	v_pk_fma_f32 v[48:49], v[48:49], s[38:39], v[52:53] op_sel_hi:[1,0,0]
	v_pk_fma_f32 v[50:51], v[50:51], s[38:39], v[52:53] op_sel_hi:[1,0,0]
	v_exp_f32_e32 v44, v44
	v_exp_f32_e32 v45, v45
	v_exp_f32_e32 v46, v46
	v_exp_f32_e32 v47, v47
	v_exp_f32_e32 v48, v48
	v_exp_f32_e32 v49, v49
	v_exp_f32_e32 v50, v50
	v_exp_f32_e32 v51, v51
	s_waitcnt lgkmcnt(0)
	v_mfma_f32_32x32x16_bf16 v[4:19], v[130:133], v[36:39], v[4:19]
	v_cvt_pk_bf16_f32 v36, v44, v45
	v_cvt_pk_bf16_f32 v37, v46, v47
	v_cvt_pk_bf16_f32 v38, v48, v49
	v_cvt_pk_bf16_f32 v39, v50, v51
	v_pk_add_f32 v[54:55], v[44:45], v[54:55]
	s_waitcnt lgkmcnt(0)
	v_mfma_f32_32x32x16_bf16 v[20:35], v[134:137], v[36:39], v[20:35]
	v_add_f32_e64 v54, v46, v54
	v_add_f32_e64 v55, v47, v55
	v_add_f32_e64 v54, v48, v54
	v_add_f32_e64 v55, v49, v55
	v_pk_add_f32 v[52:53], v[50:51], v[54:55]
	s_nop 0
	v_add_f32_e32 v52, v52, v53
	s_waitcnt lgkmcnt(0)
	v_mfma_f32_32x32x16_bf16 v[4:19], v[138:141], v[36:39], v[4:19]
	ds_bpermute_b32 v53, v110, v52
	s_waitcnt lgkmcnt(0)
	v_add_f32_e32 v52, v52, v53
	v_add_f32_e32 v113, v113, v52

; DI float fexp2(float x) { return __builtin_amdgcn_exp2f(x); }
; DI float xhalf_max(float v) { return fmaxf(v, __shfl_xor(v, 32)); }
; DI float xhalf_sum(float v) { return v + __shfl_xor(v, 32); }
; DI void tile_online(AState& st, const LAS bf16* Kt, int KP, const LAS bf16* Vt, int VP, const bf16x8 (&qf)[4], int kbase, int lo, int hi, bool flag, int r, int h) {
;     ...
;         for (int reg = 0; reg < 16; ++reg) mx = fmaxf(mx, s[reg]);
;     }
;     mx = any ? mx : -__builtin_inff();
;     mx = xhalf_max(mx);
;     if (__ballot(mx > st.m + 5.5f) != 0ull) {
;         const float mn2 = fmaxf(st.m, mx), alpha = fexp2((st.m - mn2) * LOG2E);
;         st.l = st.l * alpha; st.o0 = st.o0 * alpha; st.o1 = st.o1 * alpha; st.m = mn2;
;     }
;     const float mn = st.m;
;     const float bias = any ? -mn * LOG2E : -__builtin_inff();
;     f32x2 sum2 = {0.f, 0.f}; const f32x2 b2 = {bias, bias}, l2 = {LOG2E, LOG2E};
; #pragma unroll
;     for (int reg = 0; reg < 16; reg += 2) { f32x2 t = {s[reg], s[reg + 1]}; t = __builtin_elementwise_fma(t, l2, b2);
;         t[0] = fexp2(t[0]); t[1] = fexp2(t[1]); s[reg] = t[0]; s[reg + 1] = t[1]; sum2 = sum2 + t; }
;     st.l += xhalf_sum(sum2[0] + sum2[1]);
;     pv_tile32(st.o0, st.o1, Vt, VP, s, r + 32 * h);
.LBB0_1663:
	s_nop 9
	v_max3_f32 v2, v52, s40, v53
	v_max3_f32 v2, v2, v54, v55
	v_max3_f32 v2, v2, v56, v57
	v_max3_f32 v2, v2, v58, v59
	v_max3_f32 v2, v2, v60, v61
	v_max3_f32 v2, v2, v62, v63
	v_max3_f32 v2, v2, v64, v65
	v_max3_f32 v2, v2, v66, v67
	v_cndmask_b32_e64 v2, v231, v2, s[2:3]
	ds_bpermute_b32 v36, v110, v2
	v_max_f32_e32 v2, v2, v2
	s_waitcnt lgkmcnt(0)
	v_max_f32_e32 v36, v36, v36
	v_max_f32_e32 v2, v2, v36
	v_add_f32_e32 v36, 0x40b00000, v115
	v_cmp_gt_f32_e32 vcc, v2, v36
	s_cbranch_vccz .Lnc_exp_2
	v_max_f32_e32 v2, v2, v2
	v_max_f32_e32 v36, v115, v115
	v_max_f32_e32 v36, v36, v2
	v_sub_f32_e32 v2, v115, v36
	v_mul_f32_e32 v2, 0x3fb8aa3b, v2
	v_exp_f32_e32 v2, v2
	v_mov_b32_e32 v115, v36
	v_mul_f32_e32 v113, v113, v2
	v_pk_mul_f32 v[34:35], v[34:35], v[2:3] op_sel_hi:[1,0]
	v_pk_mul_f32 v[32:33], v[32:33], v[2:3] op_sel_hi:[1,0]
	v_pk_mul_f32 v[30:31], v[30:31], v[2:3] op_sel_hi:[1,0]
	v_pk_mul_f32 v[28:29], v[28:29], v[2:3] op_sel_hi:[1,0]
	v_pk_mul_f32 v[26:27], v[26:27], v[2:3] op_sel_hi:[1,0]
	v_pk_mul_f32 v[24:25], v[24:25], v[2:3] op_sel_hi:[1,0]
	v_pk_mul_f32 v[22:23], v[22:23], v[2:3] op_sel_hi:[1,0]
	v_pk_mul_f32 v[20:21], v[20:21], v[2:3] op_sel_hi:[1,0]
	v_pk_mul_f32 v[18:19], v[18:19], v[2:3] op_sel_hi:[1,0]
	v_pk_mul_f32 v[16:17], v[16:17], v[2:3] op_sel_hi:[1,0]
	v_pk_mul_f32 v[14:15], v[14:15], v[2:3] op_sel_hi:[1,0]
	v_pk_mul_f32 v[12:13], v[12:13], v[2:3] op_sel_hi:[1,0]
	v_pk_mul_f32 v[10:11], v[10:11], v[2:3] op_sel_hi:[1,0]
	v_pk_mul_f32 v[8:9], v[8:9], v[2:3] op_sel_hi:[1,0]
	v_pk_mul_f32 v[6:7], v[6:7], v[2:3] op_sel_hi:[1,0]
	v_pk_mul_f32 v[4:5], v[4:5], v[2:3] op_sel_hi:[1,0]
.Lnc_exp_2:
	v_mul_f32_e32 v2, 0xbfb8aa3b, v115
	v_cndmask_b32_e64 v2, v231, v2, s[2:3]
	v_pk_fma_f32 v[52:53], v[52:53], s[38:39], v[2:3] op_sel_hi:[1,0,0]
	v_pk_fma_f32 v[54:55], v[54:55], s[38:39], v[2:3] op_sel_hi:[1,0,0]
	v_exp_f32_e32 v52, v52
	v_exp_f32_e32 v53, v53
	v_exp_f32_e32 v54, v54
	v_exp_f32_e32 v55, v55
	v_pk_fma_f32 v[56:57], v[56:57], s[38:39], v[2:3] op_sel_hi:[1,0,0]
	v_pk_fma_f32 v[58:59], v[58:59], s[38:39], v[2:3] op_sel_hi:[1,0,0]
	v_exp_f32_e32 v56, v56
	v_exp_f32_e32 v57, v57
	v_exp_f32_e32 v58, v58
	v_exp_f32_e32 v59, v59
	v_pk_add_f32 v[36:37], v[52:53], 0 op_sel_hi:[1,0]
	v_cvt_pk_bf16_f32 v52, v52, v53
	v_pk_add_f32 v[36:37], v[54:55], v[36:37]
	v_cvt_pk_bf16_f32 v53, v54, v55
	v_pk_add_f32 v[36:37], v[56:57], v[36:37]
	v_cvt_pk_bf16_f32 v54, v56, v57
	v_pk_add_f32 v[36:37], v[58:59], v[36:37]
	v_cvt_pk_bf16_f32 v55, v58, v59
	s_nop 1
	s_waitcnt lgkmcnt(0)
	v_mfma_f32_32x32x16_bf16 v[20:35], v[126:129], v[52:55], v[20:35]
	v_fma_f32 v60, v60, s38, v2
	v_fma_f32 v61, v61, s38, v2
	v_fma_f32 v62, v62, s38, v2
	v_fma_f32 v63, v63, s38, v2
	v_pk_fma_f32 v[64:65], v[64:65], s[38:39], v[2:3] op_sel_hi:[1,0,0]
	v_pk_fma_f32 v[66:67], v[66:67], s[38:39], v[2:3] op_sel_hi:[1,0,0]
	v_exp_f32_e32 v60, v60
	v_exp_f32_e32 v61, v61
	v_exp_f32_e32 v62, v62
	v_exp_f32_e32 v63, v63
	v_exp_f32_e32 v64, v64
	v_exp_f32_e32 v65, v65
	v_exp_f32_e32 v66, v66
	v_exp_f32_e32 v67, v67
	s_waitcnt lgkmcnt(0)
	v_mfma_f32_32x32x16_bf16 v[4:19], v[130:133], v[52:55], v[4:19]
	v_cvt_pk_bf16_f32 v52, v60, v61
	v_cvt_pk_bf16_f32 v53, v62, v63
	v_cvt_pk_bf16_f32 v54, v64, v65
	v_cvt_pk_bf16_f32 v55, v66, v67
	v_pk_add_f32 v[36:37], v[60:61], v[36:37]
	s_waitcnt lgkmcnt(0)
	v_mfma_f32_32x32x16_bf16 v[20:35], v[134:137], v[52:55], v[20:35]
	v_add_f32_e64 v36, v62, v36
	v_add_f32_e64 v37, v63, v37
	v_add_f32_e64 v36, v64, v36
	v_add_f32_e64 v37, v65, v37
	v_pk_add_f32 v[36:37], v[66:67], v[36:37]
	s_nop 0
	v_add_f32_e32 v2, v36, v37
	s_waitcnt lgkmcnt(0)
	v_mfma_f32_32x32x16_bf16 v[4:19], v[138:141], v[52:55], v[4:19]
	ds_bpermute_b32 v36, v110, v2
	s_waitcnt lgkmcnt(0)
	v_add_f32_e32 v2, v2, v36
	v_add_f32_e32 v113, v113, v2
	s_branch .LBB0_1667

; DI float fexp2(float x) { return __builtin_amdgcn_exp2f(x); }
; DI float xhalf_sum(float v) { return v + __shfl_xor(v, 32); }
; DI void tile_online(AState& st, const LAS bf16* Kt, int KP, const LAS bf16* Vt, int VP, const bf16x8 (&qf)[4], int kbase, int lo, int hi, bool flag, int r, int h) {
;     ...
;     const float mn = st.m;
;     const float bias = any ? -mn * LOG2E : -__builtin_inff();
;     f32x2 sum2 = {0.f, 0.f}; const f32x2 b2 = {bias, bias}, l2 = {LOG2E, LOG2E};
; #pragma unroll
;     for (int reg = 0; reg < 16; reg += 2) { f32x2 t = {s[reg], s[reg + 1]}; t = __builtin_elementwise_fma(t, l2, b2);
;         t[0] = fexp2(t[0]); t[1] = fexp2(t[1]); s[reg] = t[0]; s[reg + 1] = t[1]; sum2 = sum2 + t; }
;     st.l += xhalf_sum(sum2[0] + sum2[1]);
;     pv_tile32(st.o0, st.o1, Vt, VP, s, r + 32 * h);
.LBB0_1666:
	v_mul_f32_e32 v2, 0xbfb8aa3b, v115
	v_cndmask_b32_e64 v2, v231, v2, s[2:3]
	v_pk_fma_f32 v[36:37], v[36:37], s[38:39], v[2:3] op_sel_hi:[1,0,0]
	v_pk_fma_f32 v[38:39], v[38:39], s[38:39], v[2:3] op_sel_hi:[1,0,0]
	v_exp_f32_e32 v36, v36
	v_exp_f32_e32 v37, v37
	v_exp_f32_e32 v38, v38
	v_exp_f32_e32 v39, v39
	v_pk_fma_f32 v[40:41], v[40:41], s[38:39], v[2:3] op_sel_hi:[1,0,0]
	v_pk_fma_f32 v[42:43], v[42:43], s[38:39], v[2:3] op_sel_hi:[1,0,0]
	v_exp_f32_e32 v40, v40
	v_exp_f32_e32 v41, v41
	v_exp_f32_e32 v42, v42
	v_exp_f32_e32 v43, v43
	v_pk_add_f32 v[52:53], v[36:37], 0 op_sel_hi:[1,0]
	v_cvt_pk_bf16_f32 v36, v36, v37
	v_pk_add_f32 v[52:53], v[38:39], v[52:53]
	v_cvt_pk_bf16_f32 v37, v38, v39
	v_pk_add_f32 v[52:53], v[40:41], v[52:53]
	v_cvt_pk_bf16_f32 v38, v40, v41
	v_pk_add_f32 v[52:53], v[42:43], v[52:53]
	v_cvt_pk_bf16_f32 v39, v42, v43
	s_nop 1
	s_waitcnt lgkmcnt(0)
	v_mfma_f32_32x32x16_bf16 v[20:35], v[126:129], v[36:39], v[20:35]
	v_fma_f32 v44, v44, s38, v2
	v_fma_f32 v45, v45, s38, v2
	v_fma_f32 v46, v46, s38, v2
	v_fma_f32 v47, v47, s38, v2
	v_pk_fma_f32 v[48:49], v[48:49], s[38:39], v[2:3] op_sel_hi:[1,0,0]
	v_pk_fma_f32 v[50:51], v[50:51], s[38:39], v[2:3] op_sel_hi:[1,0,0]
	v_exp_f32_e32 v44, v44
	v_exp_f32_e32 v45, v45
	v_exp_f32_e32 v46, v46
	v_exp_f32_e32 v47, v47
	v_exp_f32_e32 v48, v48
	v_exp_f32_e32 v49, v49
	v_exp_f32_e32 v50, v50
	v_exp_f32_e32 v51, v51
	s_waitcnt lgkmcnt(0)
	v_mfma_f32_32x32x16_bf16 v[4:19], v[130:133], v[36:39], v[4:19]
	v_cvt_pk_bf16_f32 v36, v44, v45
	v_cvt_pk_bf16_f32 v37, v46, v47
	v_cvt_pk_bf16_f32 v38, v48, v49
	v_cvt_pk_bf16_f32 v39, v50, v51
	v_pk_add_f32 v[52:53], v[44:45], v[52:53]
	s_waitcnt lgkmcnt(0)
	v_mfma_f32_32x32x16_bf16 v[20:35], v[134:137], v[36:39], v[20:35]
	v_add_f32_e64 v52, v46, v52
	v_add_f32_e64 v53, v47, v53
	v_add_f32_e64 v52, v48, v52
	v_add_f32_e64 v53, v49, v53
	v_pk_add_f32 v[52:53], v[50:51], v[52:53]
	s_nop 0
	v_add_f32_e32 v2, v52, v53
	s_waitcnt lgkmcnt(0)
	v_mfma_f32_32x32x16_bf16 v[4:19], v[138:141], v[36:39], v[4:19]
	ds_bpermute_b32 v52, v110, v2
	s_waitcnt lgkmcnt(0)
	v_add_f32_e32 v2, v2, v52
	v_add_f32_e32 v113, v113, v2

; DI float fexp2(float x) { return __builtin_amdgcn_exp2f(x); }
; DI float xhalf_sum(float v) { return v + __shfl_xor(v, 32); }
; DI void tile_online(AState& st, const LAS bf16* Kt, int KP, const LAS bf16* Vt, int VP, const bf16x8 (&qf)[4], int kbase, int lo, int hi, bool flag, int r, int h) {
;     ...
;     const float mn = st.m;
;     const float bias = any ? -mn * LOG2E : -__builtin_inff();
;     f32x2 sum2 = {0.f, 0.f}; const f32x2 b2 = {bias, bias}, l2 = {LOG2E, LOG2E};
; #pragma unroll
;     for (int reg = 0; reg < 16; reg += 2) { f32x2 t = {s[reg], s[reg + 1]}; t = __builtin_elementwise_fma(t, l2, b2);
;         t[0] = fexp2(t[0]); t[1] = fexp2(t[1]); s[reg] = t[0]; s[reg + 1] = t[1]; sum2 = sum2 + t; }
;     st.l += xhalf_sum(sum2[0] + sum2[1]);
;     pv_tile32(st.o0, st.o1, Vt, VP, s, r + 32 * h);
.LBB0_1684:
	v_mul_f32_e32 v2, 0xbfb8aa3b, v116
	v_cndmask_b32_e64 v2, v231, v2, s[0:1]
	v_pk_fma_f32 v[36:37], v[36:37], s[38:39], v[2:3] op_sel_hi:[1,0,0]
	v_pk_fma_f32 v[38:39], v[38:39], s[38:39], v[2:3] op_sel_hi:[1,0,0]
	v_exp_f32_e32 v36, v36
	v_exp_f32_e32 v37, v37
	v_exp_f32_e32 v38, v38
	v_exp_f32_e32 v39, v39
	v_pk_fma_f32 v[40:41], v[40:41], s[38:39], v[2:3] op_sel_hi:[1,0,0]
	v_pk_fma_f32 v[42:43], v[42:43], s[38:39], v[2:3] op_sel_hi:[1,0,0]
	v_exp_f32_e32 v40, v40
	v_exp_f32_e32 v41, v41
	v_exp_f32_e32 v42, v42
	v_exp_f32_e32 v43, v43
	v_pk_add_f32 v[52:53], v[36:37], 0 op_sel_hi:[1,0]
	v_cvt_pk_bf16_f32 v36, v36, v37
	v_pk_add_f32 v[52:53], v[38:39], v[52:53]
	v_cvt_pk_bf16_f32 v37, v38, v39
	v_pk_add_f32 v[52:53], v[40:41], v[52:53]
	v_cvt_pk_bf16_f32 v38, v40, v41
	v_pk_add_f32 v[52:53], v[42:43], v[52:53]
	v_cvt_pk_bf16_f32 v39, v42, v43
	s_nop 1
	s_waitcnt lgkmcnt(0)
	v_mfma_f32_32x32x16_bf16 v[20:35], v[126:129], v[36:39], v[20:35]
	v_fma_f32 v44, v44, s38, v2
	v_fma_f32 v45, v45, s38, v2
	v_fma_f32 v46, v46, s38, v2
	v_fma_f32 v47, v47, s38, v2
	v_pk_fma_f32 v[48:49], v[48:49], s[38:39], v[2:3] op_sel_hi:[1,0,0]
	v_pk_fma_f32 v[50:51], v[50:51], s[38:39], v[2:3] op_sel_hi:[1,0,0]
	v_exp_f32_e32 v44, v44
	v_exp_f32_e32 v45, v45
	v_exp_f32_e32 v46, v46
	v_exp_f32_e32 v47, v47
	v_exp_f32_e32 v48, v48
	v_exp_f32_e32 v49, v49
	v_exp_f32_e32 v50, v50
	v_exp_f32_e32 v51, v51
	s_waitcnt lgkmcnt(0)
	v_mfma_f32_32x32x16_bf16 v[4:19], v[130:133], v[36:39], v[4:19]
	v_cvt_pk_bf16_f32 v36, v44, v45
	v_cvt_pk_bf16_f32 v37, v46, v47
	v_cvt_pk_bf16_f32 v38, v48, v49
	v_cvt_pk_bf16_f32 v39, v50, v51
	v_pk_add_f32 v[52:53], v[44:45], v[52:53]
	s_waitcnt lgkmcnt(0)
	v_mfma_f32_32x32x16_bf16 v[20:35], v[134:137], v[36:39], v[20:35]
	v_add_f32_e64 v52, v46, v52
	v_add_f32_e64 v53, v47, v53
	v_add_f32_e64 v52, v48, v52
	v_add_f32_e64 v53, v49, v53
	v_pk_add_f32 v[52:53], v[50:51], v[52:53]
	s_nop 0
	v_add_f32_e32 v2, v52, v53
	s_waitcnt lgkmcnt(0)
	v_mfma_f32_32x32x16_bf16 v[4:19], v[138:141], v[36:39], v[4:19]
	ds_bpermute_b32 v52, v110, v2
	s_waitcnt lgkmcnt(0)
	v_add_f32_e32 v2, v2, v52
	v_add_f32_e32 v111, v111, v2

; DI float fexp2(float x) { return __builtin_amdgcn_exp2f(x); }
; DI float xhalf_max(float v) { return fmaxf(v, __shfl_xor(v, 32)); }
; DI float xhalf_sum(float v) { return v + __shfl_xor(v, 32); }
; DI void tile_online(AState& st, const LAS bf16* Kt, int KP, const LAS bf16* Vt, int VP, const bf16x8 (&qf)[4], int kbase, int lo, int hi, bool flag, int r, int h) {
;     ...
;         for (int reg = 0; reg < 16; ++reg) mx = fmaxf(mx, s[reg]);
;     }
;     mx = any ? mx : -__builtin_inff();
;     mx = xhalf_max(mx);
;     if (__ballot(mx > st.m + 5.5f) != 0ull) {
;         const float mn2 = fmaxf(st.m, mx), alpha = fexp2((st.m - mn2) * LOG2E);
;         st.l = st.l * alpha; st.o0 = st.o0 * alpha; st.o1 = st.o1 * alpha; st.m = mn2;
;     }
;     const float mn = st.m;
;     const float bias = any ? -mn * LOG2E : -__builtin_inff();
;     f32x2 sum2 = {0.f, 0.f}; const f32x2 b2 = {bias, bias}, l2 = {LOG2E, LOG2E};
; #pragma unroll
;     for (int reg = 0; reg < 16; reg += 2) { f32x2 t = {s[reg], s[reg + 1]}; t = __builtin_elementwise_fma(t, l2, b2);
;         t[0] = fexp2(t[0]); t[1] = fexp2(t[1]); s[reg] = t[0]; s[reg + 1] = t[1]; sum2 = sum2 + t; }
;     st.l += xhalf_sum(sum2[0] + sum2[1]);
;     pv_tile32(st.o0, st.o1, Vt, VP, s, r + 32 * h);
.LBB0_1696:
	s_nop 9
	v_max3_f32 v2, v52, s40, v53
	v_max3_f32 v2, v2, v54, v55
	v_max3_f32 v2, v2, v56, v57
	v_max3_f32 v2, v2, v58, v59
	v_max3_f32 v2, v2, v60, v61
	v_max3_f32 v2, v2, v62, v63
	v_max3_f32 v2, v2, v64, v65
	v_max3_f32 v2, v2, v66, v67
	v_cndmask_b32_e64 v2, v231, v2, s[0:1]
	ds_bpermute_b32 v36, v110, v2
	v_max_f32_e32 v2, v2, v2
	s_waitcnt lgkmcnt(0)
	v_max_f32_e32 v36, v36, v36
	v_max_f32_e32 v2, v2, v36
	v_add_f32_e32 v36, 0x40b00000, v116
	v_cmp_gt_f32_e32 vcc, v2, v36
	s_cbranch_vccz .Lnc_exp_4
	v_max_f32_e32 v2, v2, v2
	v_max_f32_e32 v36, v116, v116
	v_max_f32_e32 v36, v36, v2
	v_sub_f32_e32 v2, v116, v36
	v_mul_f32_e32 v2, 0x3fb8aa3b, v2
	v_exp_f32_e32 v2, v2
	v_mov_b32_e32 v116, v36
	v_mul_f32_e32 v111, v111, v2
	v_pk_mul_f32 v[34:35], v[34:35], v[2:3] op_sel_hi:[1,0]
	v_pk_mul_f32 v[32:33], v[32:33], v[2:3] op_sel_hi:[1,0]
	v_pk_mul_f32 v[30:31], v[30:31], v[2:3] op_sel_hi:[1,0]
	v_pk_mul_f32 v[28:29], v[28:29], v[2:3] op_sel_hi:[1,0]
	v_pk_mul_f32 v[26:27], v[26:27], v[2:3] op_sel_hi:[1,0]
	v_pk_mul_f32 v[24:25], v[24:25], v[2:3] op_sel_hi:[1,0]
	v_pk_mul_f32 v[22:23], v[22:23], v[2:3] op_sel_hi:[1,0]
	v_pk_mul_f32 v[20:21], v[20:21], v[2:3] op_sel_hi:[1,0]
	v_pk_mul_f32 v[18:19], v[18:19], v[2:3] op_sel_hi:[1,0]
	v_pk_mul_f32 v[16:17], v[16:17], v[2:3] op_sel_hi:[1,0]
	v_pk_mul_f32 v[14:15], v[14:15], v[2:3] op_sel_hi:[1,0]
	v_pk_mul_f32 v[12:13], v[12:13], v[2:3] op_sel_hi:[1,0]
	v_pk_mul_f32 v[10:11], v[10:11], v[2:3] op_sel_hi:[1,0]
	v_pk_mul_f32 v[8:9], v[8:9], v[2:3] op_sel_hi:[1,0]
	v_pk_mul_f32 v[6:7], v[6:7], v[2:3] op_sel_hi:[1,0]
	v_pk_mul_f32 v[4:5], v[4:5], v[2:3] op_sel_hi:[1,0]
.Lnc_exp_4:
	v_mul_f32_e32 v2, 0xbfb8aa3b, v116
	v_cndmask_b32_e64 v2, v231, v2, s[0:1]
	v_pk_fma_f32 v[52:53], v[52:53], s[38:39], v[2:3] op_sel_hi:[1,0,0]
	v_pk_fma_f32 v[54:55], v[54:55], s[38:39], v[2:3] op_sel_hi:[1,0,0]
	v_exp_f32_e32 v52, v52
	v_exp_f32_e32 v53, v53
	v_exp_f32_e32 v54, v54
	v_exp_f32_e32 v55, v55
	v_pk_fma_f32 v[56:57], v[56:57], s[38:39], v[2:3] op_sel_hi:[1,0,0]
	v_pk_fma_f32 v[58:59], v[58:59], s[38:39], v[2:3] op_sel_hi:[1,0,0]
	v_exp_f32_e32 v56, v56
	v_exp_f32_e32 v57, v57
	v_exp_f32_e32 v58, v58
	v_exp_f32_e32 v59, v59
	v_pk_add_f32 v[36:37], v[52:53], 0 op_sel_hi:[1,0]
	v_cvt_pk_bf16_f32 v52, v52, v53
	v_pk_add_f32 v[36:37], v[54:55], v[36:37]
	v_cvt_pk_bf16_f32 v53, v54, v55
	v_pk_add_f32 v[36:37], v[56:57], v[36:37]
	v_cvt_pk_bf16_f32 v54, v56, v57
	v_pk_add_f32 v[36:37], v[58:59], v[36:37]
	v_cvt_pk_bf16_f32 v55, v58, v59
	s_nop 1
	s_waitcnt lgkmcnt(0)
	v_mfma_f32_32x32x16_bf16 v[20:35], v[126:129], v[52:55], v[20:35]
	v_fma_f32 v60, v60, s38, v2
	v_fma_f32 v61, v61, s38, v2
	v_fma_f32 v62, v62, s38, v2
	v_fma_f32 v63, v63, s38, v2
	v_pk_fma_f32 v[64:65], v[64:65], s[38:39], v[2:3] op_sel_hi:[1,0,0]
	v_pk_fma_f32 v[66:67], v[66:67], s[38:39], v[2:3] op_sel_hi:[1,0,0]
	v_exp_f32_e32 v60, v60
	v_exp_f32_e32 v61, v61
	v_exp_f32_e32 v62, v62
	v_exp_f32_e32 v63, v63
	v_exp_f32_e32 v64, v64
	v_exp_f32_e32 v65, v65
	v_exp_f32_e32 v66, v66
	v_exp_f32_e32 v67, v67
	s_waitcnt lgkmcnt(0)
	v_mfma_f32_32x32x16_bf16 v[4:19], v[130:133], v[52:55], v[4:19]
	v_cvt_pk_bf16_f32 v52, v60, v61
	v_cvt_pk_bf16_f32 v53, v62, v63
	v_cvt_pk_bf16_f32 v54, v64, v65
	v_cvt_pk_bf16_f32 v55, v66, v67
	v_pk_add_f32 v[36:37], v[60:61], v[36:37]
	s_waitcnt lgkmcnt(0)
	v_mfma_f32_32x32x16_bf16 v[20:35], v[134:137], v[52:55], v[20:35]
	v_add_f32_e64 v36, v62, v36
	v_add_f32_e64 v37, v63, v37
	v_add_f32_e64 v36, v64, v36
	v_add_f32_e64 v37, v65, v37
	v_pk_add_f32 v[36:37], v[66:67], v[36:37]
	s_nop 0
	v_add_f32_e32 v2, v36, v37
	s_waitcnt lgkmcnt(0)
	v_mfma_f32_32x32x16_bf16 v[4:19], v[138:141], v[52:55], v[4:19]
	ds_bpermute_b32 v36, v110, v2
	s_waitcnt lgkmcnt(0)
	v_add_f32_e32 v2, v2, v36
	v_add_f32_e32 v111, v111, v2
	s_branch .LBB0_1700
